# v64 with one s_setprio flip pair per attention tile (raised from the PV block-1 burst across the tile barrier to the end of the S0 burst)
# speedup vs baseline: 1.0033x; 1.0033x over previous
; #define LAS __attribute__((address_space(3)))
; template <int MODE> __device__ __forceinline__ void attn_phase(LAS unsigned char* lds, const bf16_t* Q, const bf16_t* KF, const bf16_t* VT, bf16_t* O, const int* positions, const float* gq, int G, int bid) {
;     ...
;             for (int kt = 0; kt < ntiles; ++kt) {
;                 const bool more = (kt + 1 < ntiles);
;                 if (more && MODE < 3) { AT_GLOAD_K(kt + 1); AT_GLOAD_V(kt + 1); }
;                 if (kt <= my_last) {
;                     LAS unsigned char* kb = lds + (kt & 1) * AT_STAGE; LAS unsigned char* vb = kb + AT_KBYTES;
;     ...
;                     f32x16 s0, s1;
; #pragma unroll
;                     for (int i = 0; i < 16; ++i) s0[i] = -mrun;
;                     bf16x8 fr[8], fr2[4];
; #pragma unroll
;                     for (int kk = 0; kk < 8; ++kk) fr[kk] = *(const LAS bf16x8*)(kb + lq * AT_KP + (16 * kk + 8 * hi) * 2);
;                     __builtin_amdgcn_sched_barrier(0);
; #pragma unroll
;                     for (int kk = 0; kk < 4; ++kk) s0 = __builtin_amdgcn_mfma_f32_32x32x16_bf16(fr[kk], qf[kk], s0, 0, 0, 0);
;                     __builtin_amdgcn_sched_barrier(0);
; #pragma unroll
;                     for (int kk = 8; kk < 12; ++kk) fr2[kk - 8] = *(const LAS bf16x8*)(kb + lq * AT_KP + (16 * kk + 8 * hi) * 2);
;                     __builtin_amdgcn_sched_barrier(0);
; #pragma unroll
;                     for (int kk = 4; kk < 8; ++kk) s0 = __builtin_amdgcn_mfma_f32_32x32x16_bf16(fr[kk], qf[kk], s0, 0, 0, 0);
; #pragma unroll
;                     for (int kk = 8; kk < 12; ++kk) s0 = __builtin_amdgcn_mfma_f32_32x32x16_bf16(fr2[kk - 8], qf[kk], s0, 0, 0, 0);
;                     __builtin_amdgcn_sched_barrier(0);
; #pragma unroll
;                     for (int kk = 0; kk < 8; ++kk) fr[kk] = *(const LAS bf16x8*)(kb + (32 + lq) * AT_KP + (16 * kk + 8 * hi) * 2);
;                     __builtin_amdgcn_sched_barrier(0);
;                     float mx = fmaxf(fmaxf(s0[0], s0[1]), fmaxf(s0[2], s0[3]));
; #pragma unroll
;                     for (int i = 4; i < 16; i += 2) mx = fmaxf(mx, fmaxf(s0[i], s0[i + 1]));
;                     mx = fmaxf(mx, __shfl_xor(mx, 32));
;                     if (__any(mx > 6.0f)) AT_RESCALE(_Pragma("unroll") for (int i = 0; i < 16; ++i) s0[i] -= d_;);
.LBB0_668:
	s_add_i32 s7, s22, 1
	v_cmp_gt_i32_e64 s[10:11], s22, v244
	v_cmp_le_i32_e32 vcc, s22, v244
	s_cbranch_vccz .Lattn_idle
	s_and_saveexec_b64 s[44:45], vcc
	s_cbranch_execz .LBB0_674
	s_bitcmp1_b32 s22, 0
	s_cselect_b32 s22, 0xac00, 0
	s_add_i32 s22, s22, 0
	v_add_u32_e32 v14, s22, v223
	v_add_u32_e32 v14, v14, v204
	ds_read_b128 v[168:171], v14
	ds_read_b128 v[172:175], v14 offset:32
	ds_read_b128 v[176:179], v14 offset:64
	ds_read_b128 v[180:183], v14 offset:96
	ds_read_b128 v[184:187], v14 offset:128
	ds_read_b128 v[188:191], v14 offset:160
	ds_read_b128 v[192:195], v14 offset:192
	ds_read_b128 v[196:199], v14 offset:224
	buffer_load_dwordx4 v[10:13], v220, s[12:15], s6 offen
	buffer_load_dwordx4 v[160:163], v240, s[12:15], s6 offen
	buffer_load_dwordx4 v[164:167], v241, s[12:15], s6 offen
	s_add_i32 s60, s5, 0xff800000
	buffer_load_dwordx4 v[6:9], v221, s[16:19], s60 offen
	buffer_load_dwordx4 v[2:5], v221, s[16:19], s5 offen
	v_xor_b32_e32 v80, 0x80000000, v1
	v_mov_b32_e32 v81, v80
	v_mov_b64_e32 v[96:97], v[80:81]
	v_mov_b64_e32 v[98:99], v[80:81]
	v_mov_b64_e32 v[100:101], v[80:81]
	v_mov_b64_e32 v[102:103], v[80:81]
	v_mov_b64_e32 v[104:105], v[80:81]
	v_mov_b64_e32 v[106:107], v[80:81]
	v_mov_b64_e32 v[108:109], v[80:81]
	v_mov_b64_e32 v[110:111], v[80:81]
	s_waitcnt lgkmcnt(7)
	s_nop 0
	v_mfma_f32_32x32x16_bf16 v[96:111], v[168:171], v[112:115], v[96:111]
	s_waitcnt lgkmcnt(6)
	v_mfma_f32_32x32x16_bf16 v[96:111], v[172:175], v[116:119], v[96:111]
	s_waitcnt lgkmcnt(5)
	v_mfma_f32_32x32x16_bf16 v[96:111], v[176:179], v[120:123], v[96:111]
	s_waitcnt lgkmcnt(4)
	v_mfma_f32_32x32x16_bf16 v[96:111], v[180:183], v[124:127], v[96:111]
	ds_read_b128 v[82:85], v14 offset:256
	ds_read_b128 v[86:89], v14 offset:288
	ds_read_b128 v[90:93], v14 offset:320
	ds_read_b128 v[168:171], v14 offset:352
	s_waitcnt lgkmcnt(7)
	v_mfma_f32_32x32x16_bf16 v[96:111], v[184:187], v[128:131], v[96:111]
	s_waitcnt lgkmcnt(6)
	v_mfma_f32_32x32x16_bf16 v[96:111], v[188:191], v[132:135], v[96:111]
	s_waitcnt lgkmcnt(5)
	v_mfma_f32_32x32x16_bf16 v[96:111], v[192:195], v[136:139], v[96:111]
	s_waitcnt lgkmcnt(4)
	v_mfma_f32_32x32x16_bf16 v[96:111], v[196:199], v[140:143], v[96:111]
	s_waitcnt lgkmcnt(3)
	v_mfma_f32_32x32x16_bf16 v[96:111], v[82:85], v[148:151], v[96:111]
	s_waitcnt lgkmcnt(2)
	v_mfma_f32_32x32x16_bf16 v[96:111], v[86:89], v[156:159], v[96:111]
	s_waitcnt lgkmcnt(1)
	v_mfma_f32_32x32x16_bf16 v[96:111], v[90:93], v[144:147], v[96:111]
	s_waitcnt lgkmcnt(0)
	v_mfma_f32_32x32x16_bf16 v[96:111], v[168:171], v[152:155], v[96:111]
	s_setprio 0
	ds_read_b128 v[196:199], v14 offset:12800
	ds_read_b128 v[192:195], v14 offset:12832
	ds_read_b128 v[188:191], v14 offset:12864
	ds_read_b128 v[184:187], v14 offset:12896
	ds_read_b128 v[180:183], v14 offset:12928
	ds_read_b128 v[176:179], v14 offset:12960
	ds_read_b128 v[172:175], v14 offset:12992
	ds_read_b128 v[168:171], v14 offset:13024
	s_nop 3
	v_max3_f32 v15, v96, v97, v98
	v_max3_f32 v81, v99, v100, v101
	v_max3_f32 v82, v102, v103, v104
	v_max3_f32 v83, v105, v106, v107
	v_max3_f32 v84, v108, v109, v110
	v_max3_f32 v15, v15, v81, v111
	v_max3_f32 v15, v15, v82, v83
	v_max_f32_e32 v15, v15, v84
	v_mov_b32_e32 v81, v15
	s_nop 1
	v_permlane32_swap_b32_e32 v81, v15
	v_max_f32_e32 v15, v15, v81
	v_cmp_lt_f32_e32 vcc, s47, v15
	s_cbranch_vccz .LBB0_671
	v_max_f32_e32 v15, v15, v15
	v_max_f32_e32 v80, 0, v15
	v_exp_f32_e64 v82, -v80
	v_add_f32_e32 v1, v1, v80
	v_pk_add_f32 v[96:97], v[96:97], v[80:81] op_sel_hi:[1,0] neg_lo:[0,1] neg_hi:[0,1]
	v_pk_add_f32 v[98:99], v[98:99], v[80:81] op_sel_hi:[1,0] neg_lo:[0,1] neg_hi:[0,1]
	v_pk_mul_f32 v[78:79], v[78:79], v[82:83] op_sel_hi:[1,0]
	v_pk_mul_f32 v[76:77], v[76:77], v[82:83] op_sel_hi:[1,0]
	v_pk_mul_f32 v[74:75], v[74:75], v[82:83] op_sel_hi:[1,0]
	v_pk_mul_f32 v[72:73], v[72:73], v[82:83] op_sel_hi:[1,0]
	v_pk_mul_f32 v[70:71], v[70:71], v[82:83] op_sel_hi:[1,0]
	v_pk_mul_f32 v[68:69], v[68:69], v[82:83] op_sel_hi:[1,0]
	v_pk_mul_f32 v[66:67], v[66:67], v[82:83] op_sel_hi:[1,0]
	v_pk_mul_f32 v[64:65], v[64:65], v[82:83] op_sel_hi:[1,0]
	v_pk_mul_f32 v[62:63], v[62:63], v[82:83] op_sel_hi:[1,0]
	v_pk_mul_f32 v[60:61], v[60:61], v[82:83] op_sel_hi:[1,0]
	v_pk_mul_f32 v[58:59], v[58:59], v[82:83] op_sel_hi:[1,0]
	v_pk_mul_f32 v[56:57], v[56:57], v[82:83] op_sel_hi:[1,0]
	v_pk_mul_f32 v[54:55], v[54:55], v[82:83] op_sel_hi:[1,0]
	v_pk_mul_f32 v[52:53], v[52:53], v[82:83] op_sel_hi:[1,0]
	v_pk_mul_f32 v[50:51], v[50:51], v[82:83] op_sel_hi:[1,0]
	v_pk_mul_f32 v[48:49], v[48:49], v[82:83] op_sel_hi:[1,0]
	v_pk_mul_f32 v[46:47], v[46:47], v[82:83] op_sel_hi:[1,0]
	v_pk_mul_f32 v[44:45], v[44:45], v[82:83] op_sel_hi:[1,0]
	v_pk_mul_f32 v[42:43], v[42:43], v[82:83] op_sel_hi:[1,0]
	v_pk_mul_f32 v[40:41], v[40:41], v[82:83] op_sel_hi:[1,0]
	v_pk_mul_f32 v[38:39], v[38:39], v[82:83] op_sel_hi:[1,0]
	v_pk_mul_f32 v[36:37], v[36:37], v[82:83] op_sel_hi:[1,0]
	v_pk_mul_f32 v[34:35], v[34:35], v[82:83] op_sel_hi:[1,0]
	v_pk_mul_f32 v[32:33], v[32:33], v[82:83] op_sel_hi:[1,0]
	v_pk_mul_f32 v[30:31], v[30:31], v[82:83] op_sel_hi:[1,0]
	v_pk_mul_f32 v[28:29], v[28:29], v[82:83] op_sel_hi:[1,0]
	v_pk_mul_f32 v[26:27], v[26:27], v[82:83] op_sel_hi:[1,0]
	v_pk_mul_f32 v[24:25], v[24:25], v[82:83] op_sel_hi:[1,0]
	v_pk_mul_f32 v[22:23], v[22:23], v[82:83] op_sel_hi:[1,0]
	v_pk_mul_f32 v[20:21], v[20:21], v[82:83] op_sel_hi:[1,0]
	v_pk_mul_f32 v[18:19], v[18:19], v[82:83] op_sel_hi:[1,0]
	v_pk_mul_f32 v[16:17], v[16:17], v[82:83] op_sel_hi:[1,0]
	v_pk_add_f32 v[100:101], v[100:101], v[80:81] op_sel_hi:[1,0] neg_lo:[0,1] neg_hi:[0,1]
	v_pk_add_f32 v[102:103], v[102:103], v[80:81] op_sel_hi:[1,0] neg_lo:[0,1] neg_hi:[0,1]
	v_pk_add_f32 v[104:105], v[104:105], v[80:81] op_sel_hi:[1,0] neg_lo:[0,1] neg_hi:[0,1]
	v_pk_add_f32 v[106:107], v[106:107], v[80:81] op_sel_hi:[1,0] neg_lo:[0,1] neg_hi:[0,1]
	v_pk_add_f32 v[108:109], v[108:109], v[80:81] op_sel_hi:[1,0] neg_lo:[0,1] neg_hi:[0,1]
	v_pk_add_f32 v[110:111], v[110:111], v[80:81] op_sel_hi:[1,0] neg_lo:[0,1] neg_hi:[0,1]
	v_mul_f32_e32 v216, v216, v82
	v_xor_b32_e32 v80, 0x80000000, v1

; #define LAS __attribute__((address_space(3)))
; __device__ __forceinline__ unsigned pk2(float lo, float hi) { return pg8::cvt_pk_bf16(lo, hi); }
; #define AT_LSTORE(buf_) do { AT_LSTORE_K(buf_); AT_LSTORE_V(buf_); } while (0)
; template <int MODE> __device__ __forceinline__ void attn_phase(LAS unsigned char* lds, const bf16_t* Q, const bf16_t* KF, const bf16_t* VT, bf16_t* O, const int* positions, const float* gq, int G, int bid) {
;     ...
;                     __builtin_amdgcn_sched_barrier(0);
; #pragma unroll
;                     for (int ks = 0; ks < 2; ++ks)
; #pragma unroll
;                         for (int db = 0; db < 4; ++db) o[db] = __builtin_amdgcn_mfma_f32_32x32x16_bf16(va[ks * 4 + db], pb[ks], o[db], 0, 0, 0);
;                     float ps1 = 0.f;
; #pragma unroll
;                     for (int i = 0; i < 16; ++i) { s1[i] = __builtin_amdgcn_exp2f(s1[i]); ps1 += s1[i]; }
; #pragma unroll
;                     for (int g = 0; g < 8; ++g) { __builtin_amdgcn_sched_group_barrier(0x008, 1, 0); __builtin_amdgcn_sched_group_barrier(0x002, 4, 0); }
;                     __builtin_amdgcn_sched_barrier(0);
;                     lsum += ps1;
; #pragma unroll
;                     for (int ks = 0; ks < 2; ++ks)
; #pragma unroll
;                         for (int db = 0; db < 4; ++db) va[ks * 4 + db] = *(const LAS bf16x8*)(vb + (32 * db + lq) * AT_VP + (16 * (ks + 2) + 8 * hi) * 2);
;                     if (more && MODE < 3) AT_LSTORE((kt + 1) & 1);
;                     __builtin_amdgcn_sched_barrier(0);
; #pragma unroll
;                     for (int ks = 0; ks < 2; ++ks)
; #pragma unroll
;                         for (int q = 0; q < 4; ++q) { const unsigned pk = pk2(s1[8 * ks + 2 * q], s1[8 * ks + 2 * q + 1]); pb[ks][2 * q] = (short)(pk & 0xffff); pb[ks][2 * q + 1] = (short)(pk >> 16); }
;                     __builtin_amdgcn_sched_barrier(0);
; #pragma unroll
;                     for (int ks = 0; ks < 2; ++ks)
; #pragma unroll
;                         for (int db = 0; db < 4; ++db) o[db] = __builtin_amdgcn_mfma_f32_32x32x16_bf16(va[ks * 4 + db], pb[ks], o[db], 0, 0, 0);
.LBB0_673:
	v_cvt_pk_bf16_f32 v246, v196, v197
	v_cvt_pk_bf16_f32 v247, v194, v195
	v_cvt_pk_bf16_f32 v248, v192, v193
	v_cvt_pk_bf16_f32 v249, v198, v199
	v_cvt_pk_bf16_f32 v186, v186, v187
	v_cvt_pk_bf16_f32 v187, v190, v191
	v_cvt_pk_bf16_f32 v188, v188, v189
	v_cvt_pk_bf16_f32 v189, v184, v185
	s_nop 0
	s_waitcnt lgkmcnt(7)
	v_mfma_f32_32x32x16_bf16 v[64:79], v[180:183], v[246:249], v[64:79]
	v_exp_f32_e32 v180, v80
	v_exp_f32_e32 v181, v81
	v_exp_f32_e32 v182, v82
	v_exp_f32_e32 v183, v83
	v_add_f32_e32 v15, 0, v180
	v_add_f32_e32 v15, v181, v15
	v_add_f32_e32 v15, v182, v15
	v_add_f32_e32 v15, v183, v15
	s_waitcnt lgkmcnt(5)
	v_mfma_f32_32x32x16_bf16 v[48:63], v[176:179], v[246:249], v[48:63]
	v_exp_f32_e32 v176, v84
	v_exp_f32_e32 v177, v85
	v_exp_f32_e32 v178, v86
	v_exp_f32_e32 v179, v87
	v_add_f32_e32 v15, v176, v15
	v_add_f32_e32 v15, v177, v15
	v_add_f32_e32 v15, v178, v15
	v_add_f32_e32 v15, v179, v15
	s_waitcnt lgkmcnt(3)
	v_mfma_f32_32x32x16_bf16 v[32:47], v[172:175], v[246:249], v[32:47]
	v_exp_f32_e32 v172, v88
	v_exp_f32_e32 v173, v89
	v_exp_f32_e32 v174, v90
	v_exp_f32_e32 v175, v91
	v_add_f32_e32 v15, v172, v15
	v_add_f32_e32 v15, v173, v15
	v_add_f32_e32 v15, v174, v15
	v_add_f32_e32 v15, v175, v15
	s_waitcnt lgkmcnt(1)
	v_mfma_f32_32x32x16_bf16 v[16:31], v[168:171], v[246:249], v[16:31]
	v_exp_f32_e32 v184, v92
	v_exp_f32_e32 v185, v93
	v_exp_f32_e32 v190, v94
	v_add_f32_e32 v15, v184, v15
	v_add_f32_e32 v15, v185, v15
	v_add_f32_e32 v217, v190, v15
	v_mfma_f32_32x32x16_bf16 v[64:79], v[100:103], v[186:189], v[64:79]
	v_exp_f32_e32 v15, v95
	v_mfma_f32_32x32x16_bf16 v[48:63], v[104:107], v[186:189], v[48:63]
	v_mfma_f32_32x32x16_bf16 v[32:47], v[108:111], v[186:189], v[32:47]
	s_waitcnt lgkmcnt(0)
	v_mfma_f32_32x32x16_bf16 v[16:31], v[96:99], v[186:189], v[16:31]
	s_bitcmp1_b32 s7, 0
	s_cselect_b32 s22, 0xac00, 0
	ds_read_b128 v[80:83], v245 offset:25664
	ds_read_b128 v[84:87], v245 offset:25696
	ds_read_b128 v[88:91], v245 offset:30272
	ds_read_b128 v[92:95], v245 offset:30304
	ds_read_b128 v[96:99], v245 offset:34880
	ds_read_b128 v[100:103], v245 offset:34912
	ds_read_b128 v[104:107], v245 offset:39488
	ds_read_b128 v[108:111], v245 offset:39520
	s_add_i32 s22, s22, 0
	v_pk_add_f32 v[168:169], v[14:15], v[216:217]
	v_add_u32_e32 v14, s22, v200
	s_waitcnt vmcnt(4)
	ds_write_b128 v14, v[10:13]
	s_waitcnt vmcnt(3)
	ds_write_b128 v14, v[160:163] offset:128
	s_waitcnt vmcnt(2)
	ds_write_b128 v14, v[164:167] offset:256
	v_add_u32_e32 v14, s22, v222
	v_add_f32_e32 v216, v168, v169
	v_add_u32_e32 v168, 0x6000, v14
	v_add_u32_e32 v14, 0x8800, v14
	s_waitcnt vmcnt(1)
	ds_write2_b64 v168, v[6:7], v[8:9] offset0:128 offset1:130
	s_waitcnt vmcnt(0)
	ds_write2_b64 v14, v[2:3], v[4:5] offset1:2
	v_cvt_pk_bf16_f32 v168, v180, v181
	v_cvt_pk_bf16_f32 v169, v182, v183
	v_cvt_pk_bf16_f32 v170, v176, v177
	v_cvt_pk_bf16_f32 v171, v178, v179
	v_cvt_pk_bf16_f32 v172, v172, v173
	v_cvt_pk_bf16_f32 v173, v174, v175
	v_cvt_pk_bf16_f32 v174, v184, v185
	v_cvt_pk_bf16_f32 v175, v190, v15
	s_waitcnt lgkmcnt(12)
	s_setprio 1
	v_mfma_f32_32x32x16_bf16 v[64:79], v[80:83], v[168:171], v[64:79]
	s_waitcnt lgkmcnt(10)
	v_mfma_f32_32x32x16_bf16 v[48:63], v[88:91], v[168:171], v[48:63]
	s_waitcnt lgkmcnt(8)
	v_mfma_f32_32x32x16_bf16 v[32:47], v[96:99], v[168:171], v[32:47]
	s_waitcnt lgkmcnt(6)
	v_mfma_f32_32x32x16_bf16 v[16:31], v[104:107], v[168:171], v[16:31]
	v_mfma_f32_32x32x16_bf16 v[64:79], v[84:87], v[172:175], v[64:79]
	v_mfma_f32_32x32x16_bf16 v[48:63], v[92:95], v[172:175], v[48:63]
	v_mfma_f32_32x32x16_bf16 v[32:47], v[100:103], v[172:175], v[32:47]
	s_waitcnt lgkmcnt(5)
	v_mfma_f32_32x32x16_bf16 v[16:31], v[108:111], v[172:175], v[16:31]

; __device__ __forceinline__ const float* karg_in(int i) { karg_ptr_t kp = (karg_ptr_t)__builtin_amdgcn_kernarg_segment_ptr(); asm volatile("" : "+s"(kp)); return *(const float* __attribute__((address_space(4))) const*)(kp + 8 * i); }
; __global__ void __launch_bounds__(512, 2) fwd_megakernel(Params p) {
;     ...
;     if constexpr (PH_MASK & 512) attn_phase<0>(lds, QF, KF, R3, IG, (const int*)karg_in(1), karg_in(14), G, bid);
;     grid.sync();
.LBB0_683:
	s_setprio 0
	s_waitcnt vmcnt(0)
	s_barrier
	s_and_saveexec_b64 s[8:9], s[72:73]
	s_cbranch_execz .LBB0_693
	buffer_wbl2 sc1
	s_waitcnt vmcnt(0)
	s_load_dwordx2 s[10:11], s[0:1], 0xc8
	s_load_dword s12, s[0:1], 0xd0
	v_mov_b32_e32 v2, 0
	v_mov_b32_e32 v1, 1
	s_waitcnt lgkmcnt(0)
	s_add_u32 s10, s10, 0x100000
	s_addc_u32 s11, s11, 0
	s_mul_i32 s12, s12, 8
	global_atomic_add v2, v1, s[10:11]
